# FFN-down phases walk each XCD's row-tile groups in reverse (most recently written activations first); SwiGLU stores without nt
# speedup vs baseline: 1.0094x; 1.0094x over previous
.LBB0_234:
	s_or_b64 exec, exec, s[4:5]
	s_waitcnt lgkmcnt(0)
	s_barrier
	s_load_dwordx2 s[4:5], s[0:1], 0xa8
	v_mov_b32_e32 v8, v240
	s_waitcnt lgkmcnt(0)
	v_mov_b32_e32 v0, s5
	v_mov_b32_e32 v1, s4
	s_nop 0
	v_readfirstlane_b32 s7, v0
	v_mov_b32_e32 v0, s2
	v_readfirstlane_b32 s6, v1
	v_readfirstlane_b32 s33, v0
	v_mov_b32_e32 v0, s24
	s_cmpk_lt_i32 s33, 0x300
	s_cselect_b64 s[4:5], -1, 0
	v_readfirstlane_b32 s34, v0
	s_cmpk_gt_i32 s33, 0x2ff
	v_readfirstlane_b32 s35, v8
	s_cbranch_scc1 .LBB0_236
	s_ashr_i32 s8, s33, 31
	s_lshr_b32 s8, s8, 29
	s_add_i32 s8, s33, s8
	s_ashr_i32 s9, s8, 3
	s_and_b32 s8, s8, -8
	s_sub_i32 s8, s33, s8
	s_cmp_lt_i32 s8, 0
	s_movk_i32 s10, 0x61
	s_cselect_b32 s10, s10, 0x60
	s_mul_i32 s8, s8, s10
	s_add_i32 s8, s8, s9
	s_ashr_i32 s9, s8, 31
	s_lshr_b32 s9, s9, 27
	s_add_i32 s9, s8, s9
	s_ashr_i32 s10, s9, 5
	s_and_b32 s9, s9, 0xffe0
	s_sub_i32 s8, s8, s9
	s_bfe_i32 s9, s8, 0x80000
	s_bfe_u32 s9, s9, 0x3000c
	s_add_i32 s9, s8, s9
	s_bfe_i32 s11, s9, 0x80000
	s_and_b32 s9, s9, 0xf8
	s_sub_i32 s8, s8, s9
	s_lshl_b32 s10, s10, 3
	s_sext_i32_i16 s11, s11
	s_sext_i32_i8 s8, s8
	s_add_i32 s56, s10, s8
	s_and_b32 s88, s2, 7
	s_mul_i32 s88, s88, 24
	s_sub_i32 s56, s56, s88
	s_and_b32 s89, s56, 0x18
	s_lshl_b32 s89, s89, 1
	s_sub_i32 s56, s56, s89
	s_add_i32 s56, s56, 16
	s_add_i32 s56, s56, s88
	s_ashr_i32 s12, s11, 3

.LBB0_241:
	s_add_i32 s53, s53, 1
	s_mul_i32 s6, s53, s48
	s_mul_hi_u32 s7, s53, s34
	s_add_i32 s7, s7, s6
	s_mul_i32 s6, s53, s34
	s_add_u32 s10, s6, s33
	s_addc_u32 s11, s7, s49
	v_cmp_gt_i64_e64 s[6:7], s[10:11], v[142:143]
	v_cmp_lt_i64_e64 s[8:9], s[10:11], v[140:141]
	s_and_b64 vcc, exec, s[6:7]
	s_cbranch_vccnz .LBB0_243
	s_ashr_i32 s11, s10, 31
	s_lshr_b32 s11, s11, 29
	s_add_i32 s11, s10, s11
	s_ashr_i32 s28, s11, 3
	s_and_b32 s11, s11, -8
	s_sub_i32 s10, s10, s11
	s_cmp_lt_i32 s10, 0
	s_cselect_b32 s11, s50, 0x60
	s_mul_i32 s10, s10, s11
	s_add_i32 s10, s10, s28
	s_ashr_i32 s11, s10, 31
	s_lshr_b32 s11, s11, 27
	s_add_i32 s11, s10, s11
	s_ashr_i32 s28, s11, 5
	s_lshl_b32 s28, s28, 3
	s_sub_i32 s29, 0xc0, s28
	s_min_i32 s29, s29, 8
	s_abs_i32 s30, s29
	v_cvt_f32_u32_e32 v0, s30
	s_sub_i32 s54, 0, s30
	s_andn2_b32 s11, s11, 31
	s_sub_i32 s10, s10, s11
	v_rcp_iflag_f32_e32 v0, v0
	s_abs_i32 s11, s10
	s_xor_b32 s31, s10, s29
	s_ashr_i32 s31, s31, 31
	v_mul_f32_e32 v0, 0x4f7ffffe, v0
	v_cvt_u32_f32_e32 v0, v0
	s_nop 0
	v_readfirstlane_b32 s55, v0
	s_mul_i32 s54, s54, s55
	s_mul_hi_u32 s54, s55, s54
	s_add_i32 s55, s55, s54
	s_mul_hi_u32 s54, s11, s55
	s_mul_i32 s55, s54, s30
	s_sub_i32 s11, s11, s55
	s_add_i32 s57, s54, 1
	s_sub_i32 s55, s11, s30
	s_cmp_ge_u32 s11, s30
	s_cselect_b32 s54, s57, s54
	s_cselect_b32 s11, s55, s11
	s_add_i32 s55, s54, 1
	s_cmp_ge_u32 s11, s30
	s_cselect_b32 s11, s55, s54
	s_xor_b32 s11, s11, s31
	s_sub_i32 s54, s11, s31
	s_mul_i32 s11, s54, s29
	s_sub_i32 s10, s10, s11
	s_add_i32 s55, s28, s10
	s_and_b32 s88, s2, 7
	s_mul_i32 s88, s88, 24
	s_sub_i32 s55, s55, s88
	s_and_b32 s89, s55, 0x18
	s_lshl_b32 s89, s89, 1
	s_sub_i32 s55, s55, s89
	s_add_i32 s55, s55, 16
	s_add_i32 s55, s55, s88

.LBB0_961:
	s_ashr_i32 s6, s28, 31
	s_lshr_b32 s6, s6, 29
	s_add_i32 s6, s28, s6
	s_ashr_i32 s7, s6, 3
	s_and_b32 s6, s6, -8
	s_sub_i32 s6, s28, s6
	s_cmp_lt_i32 s6, 0
	s_movk_i32 s8, 0x61
	s_cselect_b32 s8, s8, 0x60
	s_mul_i32 s6, s6, s8
	s_add_i32 s6, s6, s7
	s_ashr_i32 s7, s6, 31
	s_lshr_b32 s7, s7, 27
	s_add_i32 s7, s6, s7
	s_ashr_i32 s8, s7, 5
	s_and_b32 s7, s7, 0xffe0
	s_sub_i32 s6, s6, s7
	s_bfe_i32 s7, s6, 0x80000
	s_bfe_u32 s7, s7, 0x3000c
	s_add_i32 s7, s6, s7
	s_bfe_i32 s9, s7, 0x80000
	s_and_b32 s7, s7, 0xf8
	s_sub_i32 s6, s6, s7
	s_lshl_b32 s8, s8, 3
	s_sext_i32_i16 s9, s9
	s_sext_i32_i8 s6, s6
	s_add_i32 s53, s8, s6
	s_and_b32 s88, s28, 7
	s_mul_i32 s88, s88, 24
	s_sub_i32 s53, s53, s88
	s_and_b32 s89, s53, 0x18
	s_lshl_b32 s89, s89, 1
	s_sub_i32 s53, s53, s89
	s_add_i32 s53, s53, 16
	s_add_i32 s53, s53, s88
	s_ashr_i32 s10, s9, 3
	s_andn2_b64 vcc, exec, s[2:3]
	s_cbranch_vccnz .LBB0_960

.LBB0_966:
	s_add_i32 s50, s50, 1
	s_mul_i32 s2, s50, s44
	s_mul_hi_u32 s3, s50, s29
	s_add_i32 s3, s3, s2
	s_mul_i32 s2, s50, s29
	s_add_u32 s6, s2, s28
	s_addc_u32 s7, s3, s45
	v_cmp_gt_i64_e64 s[2:3], s[6:7], v[144:145]
	v_cmp_lt_i64_e64 s[4:5], s[6:7], v[142:143]
	s_and_b64 vcc, exec, s[2:3]
	s_cbranch_vccnz .LBB0_968
	s_ashr_i32 s7, s6, 31
	s_lshr_b32 s7, s7, 29
	s_add_i32 s7, s6, s7
	s_ashr_i32 s24, s7, 3
	s_and_b32 s7, s7, -8
	s_sub_i32 s6, s6, s7
	s_cmp_lt_i32 s6, 0
	s_cselect_b32 s7, s46, 0x60
	s_mul_i32 s6, s6, s7
	s_add_i32 s6, s6, s24
	s_ashr_i32 s7, s6, 31
	s_lshr_b32 s7, s7, 27
	s_add_i32 s7, s6, s7
	s_ashr_i32 s24, s7, 5
	s_lshl_b32 s24, s24, 3
	s_sub_i32 s25, 0xc0, s24
	s_min_i32 s25, s25, 8
	s_abs_i32 s26, s25
	v_cvt_f32_u32_e32 v0, s26
	s_sub_i32 s51, 0, s26
	s_andn2_b32 s7, s7, 31
	s_sub_i32 s6, s6, s7
	v_rcp_iflag_f32_e32 v0, v0
	s_abs_i32 s7, s6
	s_xor_b32 s27, s6, s25
	s_ashr_i32 s27, s27, 31
	v_mul_f32_e32 v0, 0x4f7ffffe, v0
	v_cvt_u32_f32_e32 v0, v0
	s_nop 0
	v_readfirstlane_b32 s52, v0
	s_mul_i32 s51, s51, s52
	s_mul_hi_u32 s51, s52, s51
	s_add_i32 s52, s52, s51
	s_mul_hi_u32 s51, s7, s52
	s_mul_i32 s52, s51, s26
	s_sub_i32 s7, s7, s52
	s_add_i32 s54, s51, 1
	s_sub_i32 s52, s7, s26
	s_cmp_ge_u32 s7, s26
	s_cselect_b32 s51, s54, s51
	s_cselect_b32 s7, s52, s7
	s_add_i32 s52, s51, 1
	s_cmp_ge_u32 s7, s26
	s_cselect_b32 s7, s52, s51
	s_xor_b32 s7, s7, s27
	s_sub_i32 s51, s7, s27
	s_mul_i32 s7, s51, s25
	s_sub_i32 s6, s6, s7
	s_add_i32 s52, s24, s6
	s_and_b32 s88, s28, 7
	s_mul_i32 s88, s88, 24
	s_sub_i32 s52, s52, s88
	s_and_b32 s89, s52, 0x18
	s_lshl_b32 s89, s89, 1
	s_sub_i32 s52, s52, s89
	s_add_i32 s52, s52, 16
	s_add_i32 s52, s52, s88
